# ssd pass1/pass3 staging loops: conv tap loads issued together, pass1 tap weights kept in registers
# speedup vs baseline: 1.0217x; 1.0044x over previous
.LBB0_931:
	s_or_b64 exec, exec, s[4:5]
	v_lshlrev_b32_e32 v1, 3, v40
	v_and_b32_e32 v19, 0x78, v1
	v_lshl_or_b32 v2, s14, 7, v19
	v_or_b32_e32 v20, 0x400, v2
	v_lshlrev_b32_e32 v10, 2, v20
	global_load_dwordx4 v[2:5], v10, s[22:23] offset:16
	global_load_dwordx4 v[6:9], v10, s[22:23]
	v_ashrrev_i32_e32 v18, 4, v40
	v_mov_b32_e32 v11, v0
	v_lshl_add_u64 v[10:11], s[20:21], 0, v[10:11]
	s_mov_b64 s[4:5], 0x1800
	v_mul_u32_u24_e32 v19, 0x110, v19
	v_lshlrev_b32_e32 v21, 1, v18
	s_add_u32 s40, s8, s10
	v_lshl_add_u64 v[12:13], v[10:11], 0, s[4:5]
	s_mov_b64 s[4:5], 0x3000
	v_add3_u32 v38, v19, v21, 0
	s_addc_u32 s41, s9, 0
	v_ashrrev_i32_e32 v19, 31, v18
	v_lshl_add_u64 v[14:15], v[10:11], 0, s[4:5]
	s_mov_b64 s[4:5], 0x4800
	v_add_u32_e32 v39, s10, v18
	v_lshl_add_u64 v[18:19], s[40:41], 0, v[18:19]
	v_lshlrev_b32_e32 v20, 1, v20
	v_mov_b32_e32 v21, v0
	v_lshl_add_u64 v[16:17], v[10:11], 0, s[4:5]
	v_mad_u64_u32 v[20:21], s[4:5], v18, s84, v[20:21]
	v_mad_i32_i24 v21, v19, s84, v21
	s_mov_b32 s7, s9
	v_lshl_add_u64 v[18:19], s[2:3], 0, v[20:21]
	s_mov_b64 s[4:5], 0
	global_load_dwordx4 v[50:53], v[10:11], off
	global_load_dwordx4 v[54:57], v[10:11], off offset:16
	global_load_dwordx4 v[58:61], v[12:13], off
	global_load_dwordx4 v[62:65], v[12:13], off offset:16
	global_load_dwordx4 v[66:69], v[14:15], off
	global_load_dwordx4 v[70:73], v[14:15], off offset:16
	global_load_dwordx4 v[74:77], v[16:17], off
	global_load_dwordx4 v[78:81], v[16:17], off offset:16
	s_branch .LBB0_933

.LBB0_933:
	v_lshl_add_u64 v[22:23], v[18:19], 0, s[4:5]
	v_mov_b32_e32 v82, 0
	v_mov_b32_e32 v83, 0
	v_mov_b32_e32 v84, 0
	v_mov_b32_e32 v85, 0
	v_mov_b32_e32 v86, 0
	v_mov_b32_e32 v87, 0
	v_mov_b32_e32 v88, 0
	v_mov_b32_e32 v89, 0
	v_mov_b32_e32 v90, 0
	v_mov_b32_e32 v91, 0
	v_mov_b32_e32 v92, 0
	v_mov_b32_e32 v93, 0
	v_add_co_u32_e32 v42, vcc, 0x3201000, v22
	s_nop 1
	v_addc_co_u32_e32 v43, vcc, 0, v23, vcc
	global_load_dwordx4 v[94:97], v[42:43], off offset:2048
	v_cmp_lt_i32_e32 vcc, 0, v39
	s_and_saveexec_b64 s[8:9], vcc
	s_cbranch_execz .Lp1s_t2
	v_add_co_u32_e32 v42, vcc, 0x31ff000, v22
	s_nop 1
	v_addc_co_u32_e32 v43, vcc, 0, v23, vcc
	global_load_dwordx4 v[90:93], v[42:43], off offset:1024
.Lp1s_t2:
	s_or_b64 exec, exec, s[8:9]
	v_cmp_lt_i32_e32 vcc, 1, v39
	s_and_saveexec_b64 s[8:9], vcc
	s_cbranch_execz .Lp1s_t1
	v_add_co_u32_e32 v42, vcc, 0x31fd000, v22
	s_nop 1
	v_addc_co_u32_e32 v43, vcc, 0, v23, vcc
	global_load_dwordx4 v[86:89], v[42:43], off
.Lp1s_t1:
	s_or_b64 exec, exec, s[8:9]
	v_cmp_lt_i32_e32 vcc, 2, v39
	s_and_saveexec_b64 s[8:9], vcc
	s_cbranch_execz .Lp1s_t0
	v_add_co_u32_e32 v42, vcc, 0x31fa000, v22
	s_nop 1
	v_addc_co_u32_e32 v43, vcc, 0, v23, vcc
	global_load_dwordx4 v[82:85], v[42:43], off offset:3072
.Lp1s_t0:
	s_or_b64 exec, exec, s[8:9]
	s_waitcnt vmcnt(0)
	v_lshlrev_b32_e32 v42, 16, v82
	v_and_b32_e32 v43, 0xffff0000, v82
	v_pk_fma_f32 v[24:25], v[50:51], v[42:43], v[6:7]
	v_lshlrev_b32_e32 v44, 16, v83
	v_and_b32_e32 v45, 0xffff0000, v83
	v_pk_fma_f32 v[26:27], v[52:53], v[44:45], v[8:9]
	v_lshlrev_b32_e32 v42, 16, v84
	v_and_b32_e32 v43, 0xffff0000, v84
	v_pk_fma_f32 v[30:31], v[54:55], v[42:43], v[2:3]
	v_lshlrev_b32_e32 v44, 16, v85
	v_and_b32_e32 v45, 0xffff0000, v85
	v_pk_fma_f32 v[32:33], v[56:57], v[44:45], v[4:5]
	v_lshlrev_b32_e32 v42, 16, v86
	v_and_b32_e32 v43, 0xffff0000, v86
	v_pk_fma_f32 v[24:25], v[58:59], v[42:43], v[24:25]
	v_lshlrev_b32_e32 v44, 16, v87
	v_and_b32_e32 v45, 0xffff0000, v87
	v_pk_fma_f32 v[26:27], v[60:61], v[44:45], v[26:27]
	v_lshlrev_b32_e32 v42, 16, v88
	v_and_b32_e32 v43, 0xffff0000, v88
	v_pk_fma_f32 v[30:31], v[62:63], v[42:43], v[30:31]
	v_lshlrev_b32_e32 v44, 16, v89
	v_and_b32_e32 v45, 0xffff0000, v89
	v_pk_fma_f32 v[32:33], v[64:65], v[44:45], v[32:33]
	v_lshlrev_b32_e32 v42, 16, v90
	v_and_b32_e32 v43, 0xffff0000, v90
	v_pk_fma_f32 v[24:25], v[66:67], v[42:43], v[24:25]
	v_lshlrev_b32_e32 v44, 16, v91
	v_and_b32_e32 v45, 0xffff0000, v91
	v_pk_fma_f32 v[26:27], v[68:69], v[44:45], v[26:27]
	v_lshlrev_b32_e32 v42, 16, v92
	v_and_b32_e32 v43, 0xffff0000, v92
	v_pk_fma_f32 v[30:31], v[70:71], v[42:43], v[30:31]
	v_lshlrev_b32_e32 v44, 16, v93
	v_and_b32_e32 v45, 0xffff0000, v93
	v_pk_fma_f32 v[32:33], v[72:73], v[44:45], v[32:33]
	v_lshlrev_b32_e32 v42, 16, v94
	v_and_b32_e32 v43, 0xffff0000, v94
	v_pk_fma_f32 v[36:37], v[74:75], v[42:43], v[24:25]
	v_lshlrev_b32_e32 v44, 16, v95
	v_and_b32_e32 v45, 0xffff0000, v95
	v_pk_fma_f32 v[34:35], v[76:77], v[44:45], v[26:27]
	v_lshlrev_b32_e32 v42, 16, v96
	v_and_b32_e32 v43, 0xffff0000, v96
	v_pk_fma_f32 v[28:29], v[78:79], v[42:43], v[30:31]
	v_lshlrev_b32_e32 v44, 16, v97
	v_and_b32_e32 v45, 0xffff0000, v97
	v_pk_fma_f32 v[20:21], v[80:81], v[44:45], v[32:33]
	s_mov_b64 s[8:9], exec
	s_branch .LBB0_932

.LBB0_1101:
	v_add_u32_e32 v17, s5, v86
	v_bfe_u32 v16, v17, 4, 7
	v_ashrrev_i32_e32 v2, 3, v17
	v_and_b32_e32 v2, 0xffffff00, v2
	v_or_b32_e32 v3, s86, v16
	v_mov_b64_e32 v[4:5], s[96:97]
	v_add_u32_e32 v2, v15, v2
	s_mul_i32 s10, s87, 0x2400
	v_mad_u64_u32 v[4:5], s[8:9], v3, s84, v[4:5]
	v_add_u32_e32 v5, s10, v5
	v_ashrrev_i32_e32 v3, 31, v2
	v_lshl_add_u64 v[4:5], v[2:3], 1, v[4:5]
	v_lshlrev_b64 v[2:3], 2, v[2:3]
	s_mov_b64 s[8:9], 0x1800
	v_lshl_add_u64 v[6:7], s[90:91], 0, v[2:3]
	v_lshl_add_u64 v[10:11], v[4:5], 0, s[8:9]
	v_lshl_add_u64 v[12:13], s[88:89], 0, v[2:3]
	global_load_dwordx4 v[2:5], v[6:7], off offset:16
	s_nop 0
	global_load_dwordx4 v[6:9], v[6:7], off
	v_or_b32_e32 v18, s12, v16
	global_load_dwordx4 v[34:37], v[12:13], off
	global_load_dwordx4 v[38:41], v[12:13], off offset:16
	s_mov_b64 s[8:9], 0x1800
	v_lshl_add_u64 v[88:89], v[12:13], 0, s[8:9]
	global_load_dwordx4 v[42:45], v[88:89], off
	global_load_dwordx4 v[46:49], v[88:89], off offset:16
	v_lshl_add_u64 v[88:89], v[88:89], 0, s[8:9]
	global_load_dwordx4 v[50:53], v[88:89], off
	global_load_dwordx4 v[54:57], v[88:89], off offset:16
	v_lshl_add_u64 v[88:89], v[88:89], 0, s[8:9]
	global_load_dwordx4 v[58:61], v[88:89], off
	global_load_dwordx4 v[62:65], v[88:89], off offset:16
	global_load_dwordx4 v[78:81], v[10:11], off
	v_mov_b32_e32 v66, 0
	v_mov_b32_e32 v67, 0
	v_mov_b32_e32 v68, 0
	v_mov_b32_e32 v69, 0
	v_mov_b32_e32 v70, 0
	v_mov_b32_e32 v71, 0
	v_mov_b32_e32 v72, 0
	v_mov_b32_e32 v73, 0
	v_mov_b32_e32 v74, 0
	v_mov_b32_e32 v75, 0
	v_mov_b32_e32 v76, 0
	v_mov_b32_e32 v77, 0
	v_cmp_ne_u32_e32 vcc, 0, v18
	s_and_saveexec_b64 s[8:9], vcc
	s_cbranch_execz .Lp3s_t2
	v_add_co_u32_e32 v88, vcc, 0xffffe000, v10
	s_nop 1
	v_addc_co_u32_e32 v89, vcc, -1, v11, vcc
	global_load_dwordx4 v[74:77], v[88:89], off offset:-1024
.Lp3s_t2:
	s_or_b64 exec, exec, s[8:9]
	v_cmp_lt_u32_e32 vcc, 1, v18
	s_and_saveexec_b64 s[8:9], vcc
	s_cbranch_execz .Lp3s_t1
	v_add_co_u32_e32 v88, vcc, 0xffffc000, v10
	s_nop 1
	v_addc_co_u32_e32 v89, vcc, -1, v11, vcc
	global_load_dwordx4 v[70:73], v[88:89], off offset:-2048
.Lp3s_t1:
	s_or_b64 exec, exec, s[8:9]
	v_cmp_lt_u32_e32 vcc, 2, v18
	s_and_saveexec_b64 s[8:9], vcc
	s_cbranch_execz .Lp3s_t0
	v_add_co_u32_e32 v88, vcc, 0xffffa000, v10
	s_nop 1
	v_addc_co_u32_e32 v89, vcc, -1, v11, vcc
	global_load_dwordx4 v[66:69], v[88:89], off offset:-3072
.Lp3s_t0:
	s_or_b64 exec, exec, s[8:9]
	s_waitcnt vmcnt(0)
	v_lshlrev_b32_e32 v90, 16, v66
	v_and_b32_e32 v91, 0xffff0000, v66
	v_pk_fma_f32 v[6:7], v[34:35], v[90:91], v[6:7]
	v_lshlrev_b32_e32 v92, 16, v67
	v_and_b32_e32 v93, 0xffff0000, v67
	v_pk_fma_f32 v[8:9], v[36:37], v[92:93], v[8:9]
	v_lshlrev_b32_e32 v90, 16, v68
	v_and_b32_e32 v91, 0xffff0000, v68
	v_pk_fma_f32 v[2:3], v[38:39], v[90:91], v[2:3]
	v_lshlrev_b32_e32 v92, 16, v69
	v_and_b32_e32 v93, 0xffff0000, v69
	v_pk_fma_f32 v[4:5], v[40:41], v[92:93], v[4:5]
	v_lshlrev_b32_e32 v90, 16, v70
	v_and_b32_e32 v91, 0xffff0000, v70
	v_pk_fma_f32 v[6:7], v[42:43], v[90:91], v[6:7]
	v_lshlrev_b32_e32 v92, 16, v71
	v_and_b32_e32 v93, 0xffff0000, v71
	v_pk_fma_f32 v[8:9], v[44:45], v[92:93], v[8:9]
	v_lshlrev_b32_e32 v90, 16, v72
	v_and_b32_e32 v91, 0xffff0000, v72
	v_pk_fma_f32 v[2:3], v[46:47], v[90:91], v[2:3]
	v_lshlrev_b32_e32 v92, 16, v73
	v_and_b32_e32 v93, 0xffff0000, v73
	v_pk_fma_f32 v[4:5], v[48:49], v[92:93], v[4:5]
	v_lshlrev_b32_e32 v90, 16, v74
	v_and_b32_e32 v91, 0xffff0000, v74
	v_pk_fma_f32 v[6:7], v[50:51], v[90:91], v[6:7]
	v_lshlrev_b32_e32 v92, 16, v75
	v_and_b32_e32 v93, 0xffff0000, v75
	v_pk_fma_f32 v[8:9], v[52:53], v[92:93], v[8:9]
	v_lshlrev_b32_e32 v90, 16, v76
	v_and_b32_e32 v91, 0xffff0000, v76
	v_pk_fma_f32 v[2:3], v[54:55], v[90:91], v[2:3]
	v_lshlrev_b32_e32 v92, 16, v77
	v_and_b32_e32 v93, 0xffff0000, v77
	v_pk_fma_f32 v[4:5], v[56:57], v[92:93], v[4:5]
	v_lshlrev_b32_e32 v90, 16, v78
	v_and_b32_e32 v91, 0xffff0000, v78
	v_pk_fma_f32 v[6:7], v[58:59], v[90:91], v[6:7]
	v_lshlrev_b32_e32 v92, 16, v79
	v_and_b32_e32 v93, 0xffff0000, v79
	v_pk_fma_f32 v[8:9], v[60:61], v[92:93], v[8:9]
	v_lshlrev_b32_e32 v90, 16, v80
	v_and_b32_e32 v91, 0xffff0000, v80
	v_pk_fma_f32 v[2:3], v[62:63], v[90:91], v[2:3]
	v_lshlrev_b32_e32 v92, 16, v81
	v_and_b32_e32 v93, 0xffff0000, v81
	v_pk_fma_f32 v[4:5], v[64:65], v[92:93], v[4:5]
	s_movk_i32 s8, 0x800
	v_cmp_gt_u32_e32 vcc, s8, v17
	v_readlane_b32 s8, v255, 21
	s_addk_i32 s5, 0x200
	s_cmpk_eq_i32 s5, 0x1000
	v_mul_f32_e32 v90, 0xbfb8aa3b, v6
	v_mul_f32_e32 v91, 0xbfb8aa3b, v7
	v_exp_f32_e32 v90, v90
	v_exp_f32_e32 v91, v91
	v_add_f32_e32 v90, 1.0, v90
	v_add_f32_e32 v91, 1.0, v91
	v_rcp_f32_e32 v90, v90
	v_rcp_f32_e32 v91, v91
	s_nop 0
	v_pk_mul_f32 v[6:7], v[6:7], v[90:91]
	v_mul_f32_e32 v90, 0xbfb8aa3b, v8
	v_mul_f32_e32 v91, 0xbfb8aa3b, v9
	v_exp_f32_e32 v90, v90
	v_exp_f32_e32 v91, v91
	v_add_f32_e32 v90, 1.0, v90
	v_add_f32_e32 v91, 1.0, v91
	v_rcp_f32_e32 v90, v90
	v_rcp_f32_e32 v91, v91
	s_nop 0
	v_pk_mul_f32 v[8:9], v[8:9], v[90:91]
	v_mul_f32_e32 v90, 0xbfb8aa3b, v2
	v_mul_f32_e32 v91, 0xbfb8aa3b, v3
	v_exp_f32_e32 v90, v90
	v_exp_f32_e32 v91, v91
	v_add_f32_e32 v90, 1.0, v90
	v_add_f32_e32 v91, 1.0, v91
	v_rcp_f32_e32 v90, v90
	v_rcp_f32_e32 v91, v91
	s_nop 0
	v_pk_mul_f32 v[10:11], v[2:3], v[90:91]
	v_mul_f32_e32 v90, 0xbfb8aa3b, v4
	v_mul_f32_e32 v91, 0xbfb8aa3b, v5
	v_exp_f32_e32 v90, v90
	v_exp_f32_e32 v91, v91
	v_add_f32_e32 v90, 1.0, v90
	v_add_f32_e32 v91, 1.0, v91
	v_rcp_f32_e32 v90, v90
	v_rcp_f32_e32 v91, v91
	s_nop 0
	v_pk_mul_f32 v[12:13], v[4:5], v[90:91]
	v_cvt_pk_bf16_f32 v2, v6, v7
	v_mov_b32_e32 v6, s8
	v_cvt_pk_bf16_f32 v3, v8, v9
	v_cndmask_b32_e32 v6, 0, v6, vcc
	v_mul_u32_u24_e32 v7, 0x110, v16
	v_lshlrev_b32_e32 v8, 1, v14
	v_cvt_pk_bf16_f32 v4, v10, v11
	v_cvt_pk_bf16_f32 v5, v12, v13
	v_add3_u32 v6, v6, v7, v8
	ds_write_b128 v6, v[2:5]
	s_cbranch_scc0 .LBB0_1101
